# GEMM main loop: the loading wave group runs at priority 2 during the two heavy load segments (six LDS-DMA + eight ds_reads), back to 0 before the counted wait
# speedup vs baseline: 1.0057x; 1.0045x over previous
; #define PG8_STAGE(bufoff, gbase, voff) do { _Pragma("unroll") for (int _i = 0; _i < 2; ++_i) \
;         __builtin_amdgcn_global_load_lds((const unsigned*)((const char*)(gbase) + (voff)[_i]), (LAS unsigned*)(lds + (bufoff) + ldsw + _i * 8192), 16, 0, 0); } while (0)
; #define PG8_LDA(dst, b, h) do { _Pragma("unroll") for (int m = 0; m < 4; ++m) _Pragma("unroll") for (int k = 0; k < 2; ++k) dst[m][k] = *(const LAS bf16x8*)(lds + PG8_SA(b, h) + aoff + m * 2048 + k * 1024); } while (0)
; #define PG8_LDB(dst, b, h) do { _Pragma("unroll") for (int n = 0; n < 2; ++n) _Pragma("unroll") for (int k = 0; k < 2; ++k) dst[n][k] = *(const LAS bf16x8*)(lds + PG8_SB(b, h) + boff + n * 2048 + k * 1024); } while (0)
; #define PG8_MMA(ai, bj, At, Bt) do { __builtin_amdgcn_s_setprio(1); _Pragma("unroll") for (int m = 0; m < 4; ++m) _Pragma("unroll") for (int n = 0; n < 2; ++n) _Pragma("unroll") for (int k = 0; k < 2; ++k) \
;         acc[ai][bj][m][n] = __builtin_amdgcn_mfma_f32_16x16x32_bf16(Bt[n][k], At[m][k], acc[ai][bj][m][n], 0, 0, 0); __builtin_amdgcn_s_setprio(0); } while (0)
; #define PG8_WAIT_V(n) asm volatile("s_waitcnt vmcnt(" #n ")" ::: "memory")
; #define PG8_WAIT_L(n) asm volatile("s_waitcnt lgkmcnt(" #n ")" ::: "memory")
; #define PG8_BAR __builtin_amdgcn_s_barrier()
; #define PG8_SCHED __builtin_amdgcn_sched_barrier(0)
; template <class EpiT>
; __device__ __forceinline__ void gemm_phase(LAS unsigned char* lds, const Gemm g, const StaticOrder& S, const EpiT& E, int wv) {
;     ...
;         for (int t = 0; t < nt; t += 2) {
;             const bool last = (t == nt - 2);
;             const char* a1 = cA + (size_t)(t + 1) * kstep;
;             const char* a2 = last ? nA : cA + (size_t)(t + 2) * kstep; const char* b2 = last ? nB : cB + (size_t)(t + 2) * kstep;
;             const char* a3 = a2 + kstep; const char* b3 = b2 + kstep;
;             PG8_LDB(B0, 0, 0); PG8_LDB(B1, 0, 1); PG8_SCHED; PG8_LDA(At, 0, 0); PG8_STAGE(PG8_SA(1, 1), a1 + hA, voffA);
;             PG8_WAIT_V(8); PG8_WAIT_L(0); PG8_BAR; PG8_MMA(0, 0, At, B0); PG8_MMA(0, 1, At, B1); PG8_BAR; PG8_SCHED;
;             PG8_LDA(At, 0, 1); PG8_STAGE(PG8_SB(0, 0), b2, voffB); PG8_STAGE(PG8_SB(0, 1), b2 + hB, voffB); PG8_STAGE(PG8_SA(0, 0), a2, voffA);
;             PG8_WAIT_V(8); PG8_WAIT_L(0); PG8_BAR; PG8_MMA(1, 0, At, B0); PG8_MMA(1, 1, At, B1); PG8_BAR; PG8_SCHED;
.LBB0_271:
	s_add_i32 s42, s22, 2
	s_add_u32 s43, s0, 0x80
	s_addc_u32 s23, s1, 0
	s_add_i32 s64, 0, 0x10000
	s_cmp_eq_u32 s52, s22
	s_cselect_b32 s23, s19, s23
	s_cselect_b32 s22, s18, s43
	v_add_u32_e32 v0, s64, v234
	s_cselect_b32 s45, s21, s41
	s_cselect_b32 s44, s20, s40
	s_add_i32 s43, 0, 0x14000
	ds_read_b128 v[134:137], v0
	ds_read_b128 v[138:141], v0 offset:1024
	ds_read_b128 v[142:145], v0 offset:2048
	ds_read_b128 v[146:149], v0 offset:3072
	v_add_u32_e32 v0, s43, v234
	ds_read_b128 v[150:153], v0
	ds_read_b128 v[154:157], v0 offset:1024
	ds_read_b128 v[158:161], v0 offset:2048
	ds_read_b128 v[162:165], v0 offset:3072
	s_add_i32 m0, s14, 0xc000
	ds_read_b128 v[166:169], v242
	ds_read_b128 v[170:173], v242 offset:1024
	ds_read_b128 v[174:177], v242 offset:2048
	ds_read_b128 v[178:181], v242 offset:3072
	ds_read_b128 v[204:207], v242 offset:4096
	ds_read_b128 v[208:211], v242 offset:5120
	ds_read_b128 v[212:215], v242 offset:6144
	ds_read_b128 v[216:219], v242 offset:7168
	global_load_lds_dwordx4 v196, s[0:1]
	s_add_i32 m0, s14, 0xe000
	s_nop 0
	global_load_lds_dwordx4 v198, s[0:1]
	s_waitcnt vmcnt(8)
	s_waitcnt lgkmcnt(0)
	s_barrier
	s_setprio 1
	s_waitcnt lgkmcnt(0)
	v_mfma_f32_16x16x32_bf16 v[130:133], v[134:137], v[166:169], v[130:133]
	v_mfma_f32_16x16x32_bf16 v[126:129], v[142:145], v[166:169], v[126:129]
	v_mfma_f32_16x16x32_bf16 v[114:117], v[134:137], v[174:177], v[114:117]
	v_mfma_f32_16x16x32_bf16 v[110:113], v[142:145], v[174:177], v[110:113]
	v_mfma_f32_16x16x32_bf16 v[98:101], v[134:137], v[204:207], v[98:101]
	v_mfma_f32_16x16x32_bf16 v[94:97], v[142:145], v[204:207], v[94:97]
	v_mfma_f32_16x16x32_bf16 v[82:85], v[134:137], v[212:215], v[82:85]
	v_mfma_f32_16x16x32_bf16 v[78:81], v[142:145], v[212:215], v[78:81]
	v_mfma_f32_16x16x32_bf16 v[130:133], v[138:141], v[170:173], v[130:133]
	v_mfma_f32_16x16x32_bf16 v[126:129], v[146:149], v[170:173], v[126:129]
	v_mfma_f32_16x16x32_bf16 v[114:117], v[138:141], v[178:181], v[114:117]
	v_mfma_f32_16x16x32_bf16 v[110:113], v[146:149], v[178:181], v[110:113]
	v_mfma_f32_16x16x32_bf16 v[98:101], v[138:141], v[208:211], v[98:101]
	v_mfma_f32_16x16x32_bf16 v[94:97], v[146:149], v[208:211], v[94:97]
	v_mfma_f32_16x16x32_bf16 v[82:85], v[138:141], v[216:219], v[82:85]
	v_mfma_f32_16x16x32_bf16 v[78:81], v[146:149], v[216:219], v[78:81]
	s_setprio 0
	s_setprio 1
	v_mfma_f32_16x16x32_bf16 v[122:125], v[150:153], v[166:169], v[122:125]
	v_mfma_f32_16x16x32_bf16 v[118:121], v[158:161], v[166:169], v[118:121]
	v_mfma_f32_16x16x32_bf16 v[106:109], v[150:153], v[174:177], v[106:109]
	v_mfma_f32_16x16x32_bf16 v[102:105], v[158:161], v[174:177], v[102:105]
	v_mfma_f32_16x16x32_bf16 v[90:93], v[150:153], v[204:207], v[90:93]
	v_mfma_f32_16x16x32_bf16 v[86:89], v[158:161], v[204:207], v[86:89]
	v_mfma_f32_16x16x32_bf16 v[74:77], v[150:153], v[212:215], v[74:77]
	v_mfma_f32_16x16x32_bf16 v[70:73], v[158:161], v[212:215], v[70:73]
	v_mfma_f32_16x16x32_bf16 v[122:125], v[154:157], v[170:173], v[122:125]
	v_mfma_f32_16x16x32_bf16 v[118:121], v[162:165], v[170:173], v[118:121]
	v_mfma_f32_16x16x32_bf16 v[106:109], v[154:157], v[178:181], v[106:109]
	v_mfma_f32_16x16x32_bf16 v[102:105], v[162:165], v[178:181], v[102:105]
	v_mfma_f32_16x16x32_bf16 v[90:93], v[154:157], v[208:211], v[90:93]
	v_mfma_f32_16x16x32_bf16 v[86:89], v[162:165], v[208:211], v[86:89]
	v_mfma_f32_16x16x32_bf16 v[74:77], v[154:157], v[216:219], v[74:77]
	v_mfma_f32_16x16x32_bf16 v[70:73], v[162:165], v[216:219], v[70:73]
	s_setprio 0
	s_barrier
	s_add_i32 s64, s64, s13
	s_setprio 2
	s_mov_b32 m0, s64
	s_add_u32 s36, s44, 0x80
	s_addc_u32 s37, s45, 0
	ds_read_b128 v[166:169], v242 offset:16384
	ds_read_b128 v[170:173], v242 offset:17408
	ds_read_b128 v[174:177], v242 offset:18432
	ds_read_b128 v[178:181], v242 offset:19456
	ds_read_b128 v[204:207], v242 offset:20480
	ds_read_b128 v[208:211], v242 offset:21504
	ds_read_b128 v[212:215], v242 offset:22528
	ds_read_b128 v[216:219], v242 offset:23552
	global_load_lds_dwordx4 v182, s[44:45]
	s_add_i32 m0, s64, 0x2000
	s_add_i32 s43, s43, s13
	global_load_lds_dwordx4 v186, s[44:45]
	s_add_u32 s44, s44, s8
	s_addc_u32 s45, s45, 0
	s_mov_b32 m0, s43
	s_add_u32 s38, s44, 0x80
	s_addc_u32 s39, s45, 0
	global_load_lds_dwordx4 v182, s[44:45]
	s_add_i32 m0, s43, 0x2000
	s_add_u32 s46, s22, 0x80
	s_addc_u32 s47, s23, 0
	global_load_lds_dwordx4 v186, s[44:45]
	s_mov_b32 m0, s14
	s_nop 0
	global_load_lds_dwordx4 v14, s[22:23]
	s_mov_b32 m0, s15
	s_nop 0
	global_load_lds_dwordx4 v184, s[22:23]
	s_setprio 0
	s_waitcnt vmcnt(8)
	s_waitcnt lgkmcnt(0)
	s_barrier
; #define PG8_STAGE(bufoff, gbase, voff) do { _Pragma("unroll") for (int _i = 0; _i < 2; ++_i) \
;         __builtin_amdgcn_global_load_lds((const unsigned*)((const char*)(gbase) + (voff)[_i]), (LAS unsigned*)(lds + (bufoff) + ldsw + _i * 8192), 16, 0, 0); } while (0)
; #define PG8_LDA(dst, b, h) do { _Pragma("unroll") for (int m = 0; m < 4; ++m) _Pragma("unroll") for (int k = 0; k < 2; ++k) dst[m][k] = *(const LAS bf16x8*)(lds + PG8_SA(b, h) + aoff + m * 2048 + k * 1024); } while (0)
; #define PG8_LDB(dst, b, h) do { _Pragma("unroll") for (int n = 0; n < 2; ++n) _Pragma("unroll") for (int k = 0; k < 2; ++k) dst[n][k] = *(const LAS bf16x8*)(lds + PG8_SB(b, h) + boff + n * 2048 + k * 1024); } while (0)
; #define PG8_MMA(ai, bj, At, Bt) do { __builtin_amdgcn_s_setprio(1); _Pragma("unroll") for (int m = 0; m < 4; ++m) _Pragma("unroll") for (int n = 0; n < 2; ++n) _Pragma("unroll") for (int k = 0; k < 2; ++k) \
;         acc[ai][bj][m][n] = __builtin_amdgcn_mfma_f32_16x16x32_bf16(Bt[n][k], At[m][k], acc[ai][bj][m][n], 0, 0, 0); __builtin_amdgcn_s_setprio(0); } while (0)
; #define PG8_WAIT_V(n) asm volatile("s_waitcnt vmcnt(" #n ")" ::: "memory")
; #define PG8_WAIT_L(n) asm volatile("s_waitcnt lgkmcnt(" #n ")" ::: "memory")
; #define PG8_BAR __builtin_amdgcn_s_barrier()
; #define PG8_SCHED __builtin_amdgcn_sched_barrier(0)
; template <class EpiT>
; __device__ __forceinline__ void gemm_phase(LAS unsigned char* lds, const Gemm g, const StaticOrder& S, const EpiT& E, int wv) {
;     ...
;             PG8_WAIT_V(8); PG8_WAIT_L(0); PG8_BAR; PG8_MMA(1, 0, At, B0); PG8_MMA(1, 1, At, B1); PG8_BAR; PG8_SCHED;
;             PG8_LDB(B0, 1, 0); PG8_LDB(B1, 1, 1); PG8_SCHED; PG8_LDA(At, 1, 0); PG8_STAGE(PG8_SA(0, 1), a2 + hA, voffA);
;             PG8_WAIT_V(8); PG8_WAIT_L(0); PG8_BAR; PG8_MMA(0, 0, At, B0); PG8_MMA(0, 1, At, B1); PG8_BAR; PG8_SCHED;
	s_setprio 1
	s_waitcnt lgkmcnt(0)
	v_mfma_f32_16x16x32_bf16 v[66:69], v[134:137], v[166:169], v[66:69]
	v_mfma_f32_16x16x32_bf16 v[62:65], v[142:145], v[166:169], v[62:65]
	v_mfma_f32_16x16x32_bf16 v[50:53], v[134:137], v[174:177], v[50:53]
	v_mfma_f32_16x16x32_bf16 v[46:49], v[142:145], v[174:177], v[46:49]
	v_mfma_f32_16x16x32_bf16 v[34:37], v[134:137], v[204:207], v[34:37]
	v_mfma_f32_16x16x32_bf16 v[30:33], v[142:145], v[204:207], v[30:33]
	v_mfma_f32_16x16x32_bf16 v[18:21], v[134:137], v[212:215], v[18:21]
	v_mfma_f32_16x16x32_bf16 v[10:13], v[142:145], v[212:215], v[10:13]
	v_mfma_f32_16x16x32_bf16 v[66:69], v[138:141], v[170:173], v[66:69]
	v_mfma_f32_16x16x32_bf16 v[62:65], v[146:149], v[170:173], v[62:65]
	v_mfma_f32_16x16x32_bf16 v[50:53], v[138:141], v[178:181], v[50:53]
	v_mfma_f32_16x16x32_bf16 v[46:49], v[146:149], v[178:181], v[46:49]
	v_mfma_f32_16x16x32_bf16 v[34:37], v[138:141], v[208:211], v[34:37]
	v_mfma_f32_16x16x32_bf16 v[30:33], v[146:149], v[208:211], v[30:33]
	v_mfma_f32_16x16x32_bf16 v[18:21], v[138:141], v[216:219], v[18:21]
	v_mfma_f32_16x16x32_bf16 v[10:13], v[146:149], v[216:219], v[10:13]
	s_setprio 0
	s_setprio 1
	v_mfma_f32_16x16x32_bf16 v[58:61], v[150:153], v[166:169], v[58:61]
	v_mfma_f32_16x16x32_bf16 v[54:57], v[158:161], v[166:169], v[54:57]
	v_mfma_f32_16x16x32_bf16 v[42:45], v[150:153], v[174:177], v[42:45]
	v_mfma_f32_16x16x32_bf16 v[38:41], v[158:161], v[174:177], v[38:41]
	v_mfma_f32_16x16x32_bf16 v[26:29], v[150:153], v[204:207], v[26:29]
	v_mfma_f32_16x16x32_bf16 v[22:25], v[158:161], v[204:207], v[22:25]
	v_mfma_f32_16x16x32_bf16 v[6:9], v[150:153], v[212:215], v[6:9]
	v_mfma_f32_16x16x32_bf16 v[2:5], v[158:161], v[212:215], v[2:5]
	v_mfma_f32_16x16x32_bf16 v[58:61], v[154:157], v[170:173], v[58:61]
	v_mfma_f32_16x16x32_bf16 v[54:57], v[162:165], v[170:173], v[54:57]
	v_mfma_f32_16x16x32_bf16 v[42:45], v[154:157], v[178:181], v[42:45]
	v_mfma_f32_16x16x32_bf16 v[38:41], v[162:165], v[178:181], v[38:41]
	v_mfma_f32_16x16x32_bf16 v[26:29], v[154:157], v[208:211], v[26:29]
	v_mfma_f32_16x16x32_bf16 v[22:25], v[162:165], v[208:211], v[22:25]
	v_mfma_f32_16x16x32_bf16 v[6:9], v[154:157], v[216:219], v[6:9]
	v_mfma_f32_16x16x32_bf16 v[2:5], v[162:165], v[216:219], v[2:5]
	s_setprio 0
	s_barrier
	s_add_i32 s43, 0, 0x18000
	v_add_u32_e32 v0, s43, v234
	s_add_i32 s44, 0, 0x1c000
	ds_read_b128 v[134:137], v0
	ds_read_b128 v[138:141], v0 offset:1024
	ds_read_b128 v[142:145], v0 offset:2048
	ds_read_b128 v[146:149], v0 offset:3072
	v_add_u32_e32 v0, s44, v234
	ds_read_b128 v[150:153], v0
	ds_read_b128 v[154:157], v0 offset:1024
	ds_read_b128 v[158:161], v0 offset:2048
	ds_read_b128 v[162:165], v0 offset:3072
	s_add_u32 s22, s22, s4
	s_addc_u32 s23, s23, 0
	s_mov_b32 m0, s88
	ds_read_b128 v[166:169], v242 offset:32768
	ds_read_b128 v[170:173], v242 offset:33792
	ds_read_b128 v[174:177], v242 offset:34816
	ds_read_b128 v[178:181], v242 offset:35840
	ds_read_b128 v[204:207], v242 offset:36864
	ds_read_b128 v[208:211], v242 offset:37888
	ds_read_b128 v[212:215], v242 offset:38912
	ds_read_b128 v[216:219], v242 offset:39936
	global_load_lds_dwordx4 v14, s[22:23]
	s_mov_b32 m0, s89
	s_nop 0
	global_load_lds_dwordx4 v184, s[22:23]
	s_waitcnt vmcnt(8)
	s_waitcnt lgkmcnt(0)
	s_barrier
	s_setprio 1
	s_waitcnt lgkmcnt(0)
	v_mfma_f32_16x16x32_bf16 v[130:133], v[134:137], v[166:169], v[130:133]
	v_mfma_f32_16x16x32_bf16 v[126:129], v[142:145], v[166:169], v[126:129]
	v_mfma_f32_16x16x32_bf16 v[114:117], v[134:137], v[174:177], v[114:117]
	v_mfma_f32_16x16x32_bf16 v[110:113], v[142:145], v[174:177], v[110:113]
	v_mfma_f32_16x16x32_bf16 v[98:101], v[134:137], v[204:207], v[98:101]
	v_mfma_f32_16x16x32_bf16 v[94:97], v[142:145], v[204:207], v[94:97]
	v_mfma_f32_16x16x32_bf16 v[82:85], v[134:137], v[212:215], v[82:85]
	v_mfma_f32_16x16x32_bf16 v[78:81], v[142:145], v[212:215], v[78:81]
	v_mfma_f32_16x16x32_bf16 v[130:133], v[138:141], v[170:173], v[130:133]
	v_mfma_f32_16x16x32_bf16 v[126:129], v[146:149], v[170:173], v[126:129]
	v_mfma_f32_16x16x32_bf16 v[114:117], v[138:141], v[178:181], v[114:117]
	v_mfma_f32_16x16x32_bf16 v[110:113], v[146:149], v[178:181], v[110:113]
	v_mfma_f32_16x16x32_bf16 v[98:101], v[138:141], v[208:211], v[98:101]
	v_mfma_f32_16x16x32_bf16 v[94:97], v[146:149], v[208:211], v[94:97]
	v_mfma_f32_16x16x32_bf16 v[82:85], v[138:141], v[216:219], v[82:85]
	v_mfma_f32_16x16x32_bf16 v[78:81], v[146:149], v[216:219], v[78:81]
	s_setprio 0
	s_setprio 1
	v_mfma_f32_16x16x32_bf16 v[122:125], v[150:153], v[166:169], v[122:125]
	v_mfma_f32_16x16x32_bf16 v[118:121], v[158:161], v[166:169], v[118:121]
	v_mfma_f32_16x16x32_bf16 v[106:109], v[150:153], v[174:177], v[106:109]
	v_mfma_f32_16x16x32_bf16 v[102:105], v[158:161], v[174:177], v[102:105]
	v_mfma_f32_16x16x32_bf16 v[90:93], v[150:153], v[204:207], v[90:93]
	v_mfma_f32_16x16x32_bf16 v[86:89], v[158:161], v[204:207], v[86:89]
	v_mfma_f32_16x16x32_bf16 v[74:77], v[150:153], v[212:215], v[74:77]
	v_mfma_f32_16x16x32_bf16 v[70:73], v[158:161], v[212:215], v[70:73]
	v_mfma_f32_16x16x32_bf16 v[122:125], v[154:157], v[170:173], v[122:125]
	v_mfma_f32_16x16x32_bf16 v[118:121], v[162:165], v[170:173], v[118:121]
	v_mfma_f32_16x16x32_bf16 v[106:109], v[154:157], v[178:181], v[106:109]
	v_mfma_f32_16x16x32_bf16 v[102:105], v[162:165], v[178:181], v[102:105]
	v_mfma_f32_16x16x32_bf16 v[90:93], v[154:157], v[208:211], v[90:93]
	v_mfma_f32_16x16x32_bf16 v[86:89], v[162:165], v[208:211], v[86:89]
	v_mfma_f32_16x16x32_bf16 v[74:77], v[154:157], v[216:219], v[74:77]
	v_mfma_f32_16x16x32_bf16 v[70:73], v[162:165], v[216:219], v[70:73]
	s_setprio 0
	s_barrier
; #define PG8_STAGE(bufoff, gbase, voff) do { _Pragma("unroll") for (int _i = 0; _i < 2; ++_i) \
;         __builtin_amdgcn_global_load_lds((const unsigned*)((const char*)(gbase) + (voff)[_i]), (LAS unsigned*)(lds + (bufoff) + ldsw + _i * 8192), 16, 0, 0); } while (0)
; #define PG8_LDA(dst, b, h) do { _Pragma("unroll") for (int m = 0; m < 4; ++m) _Pragma("unroll") for (int k = 0; k < 2; ++k) dst[m][k] = *(const LAS bf16x8*)(lds + PG8_SA(b, h) + aoff + m * 2048 + k * 1024); } while (0)
; #define PG8_MMA(ai, bj, At, Bt) do { __builtin_amdgcn_s_setprio(1); _Pragma("unroll") for (int m = 0; m < 4; ++m) _Pragma("unroll") for (int n = 0; n < 2; ++n) _Pragma("unroll") for (int k = 0; k < 2; ++k) \
;         acc[ai][bj][m][n] = __builtin_amdgcn_mfma_f32_16x16x32_bf16(Bt[n][k], At[m][k], acc[ai][bj][m][n], 0, 0, 0); __builtin_amdgcn_s_setprio(0); } while (0)
; #define PG8_WAIT_V(n) asm volatile("s_waitcnt vmcnt(" #n ")" ::: "memory")
; #define PG8_WAIT_L(n) asm volatile("s_waitcnt lgkmcnt(" #n ")" ::: "memory")
; #define PG8_BAR __builtin_amdgcn_s_barrier()
; #define PG8_SCHED __builtin_amdgcn_sched_barrier(0)
; template <class EpiT>
; __device__ __forceinline__ void gemm_phase(LAS unsigned char* lds, const Gemm g, const StaticOrder& S, const EpiT& E, int wv) {
;     ...
;             PG8_LDA(At, 1, 1); PG8_STAGE(PG8_SB(1, 0), b3, voffB); PG8_STAGE(PG8_SB(1, 1), b3 + hB, voffB); PG8_STAGE(PG8_SA(1, 0), a3, voffA);
;             PG8_WAIT_V(8); PG8_WAIT_L(0); PG8_BAR; PG8_MMA(1, 0, At, B0); PG8_MMA(1, 1, At, B1); PG8_BAR; PG8_SCHED;
;         }
	s_add_i32 s22, s43, s13
	s_setprio 2
	s_mov_b32 m0, s22
	ds_read_b128 v[166:169], v242 offset:49152
	ds_read_b128 v[170:173], v242 offset:50176
	ds_read_b128 v[174:177], v242 offset:51200
	ds_read_b128 v[178:181], v242 offset:52224
	ds_read_b128 v[204:207], v242 offset:53248
	ds_read_b128 v[208:211], v242 offset:54272
	ds_read_b128 v[212:215], v242 offset:55296
	ds_read_b128 v[216:219], v242 offset:56320
	global_load_lds_dwordx4 v182, s[36:37]
	s_add_i32 m0, s22, 0x2000
	s_add_i32 s22, s44, s13
	global_load_lds_dwordx4 v186, s[36:37]
	s_mov_b32 m0, s22
	s_nop 0
	global_load_lds_dwordx4 v182, s[38:39]
	s_add_i32 m0, s22, 0x2000
	s_nop 0
	global_load_lds_dwordx4 v186, s[38:39]
	s_mov_b32 m0, s72
	s_nop 0
	global_load_lds_dwordx4 v14, s[46:47]
	s_mov_b32 m0, s73
	s_nop 0
	global_load_lds_dwordx4 v184, s[46:47]
	s_setprio 0
	s_waitcnt vmcnt(8)
	s_waitcnt lgkmcnt(0)
	s_barrier
	s_setprio 1
	s_waitcnt lgkmcnt(0)
	v_mfma_f32_16x16x32_bf16 v[66:69], v[134:137], v[166:169], v[66:69]
	v_mfma_f32_16x16x32_bf16 v[62:65], v[142:145], v[166:169], v[62:65]
	v_mfma_f32_16x16x32_bf16 v[50:53], v[134:137], v[174:177], v[50:53]
	v_mfma_f32_16x16x32_bf16 v[46:49], v[142:145], v[174:177], v[46:49]
	v_mfma_f32_16x16x32_bf16 v[34:37], v[134:137], v[204:207], v[34:37]
	v_mfma_f32_16x16x32_bf16 v[30:33], v[142:145], v[204:207], v[30:33]
	v_mfma_f32_16x16x32_bf16 v[18:21], v[134:137], v[212:215], v[18:21]
	v_mfma_f32_16x16x32_bf16 v[10:13], v[142:145], v[212:215], v[10:13]
	v_mfma_f32_16x16x32_bf16 v[66:69], v[138:141], v[170:173], v[66:69]
	v_mfma_f32_16x16x32_bf16 v[62:65], v[146:149], v[170:173], v[62:65]
	v_mfma_f32_16x16x32_bf16 v[50:53], v[138:141], v[178:181], v[50:53]
	v_mfma_f32_16x16x32_bf16 v[46:49], v[146:149], v[178:181], v[46:49]
	v_mfma_f32_16x16x32_bf16 v[34:37], v[138:141], v[208:211], v[34:37]
	v_mfma_f32_16x16x32_bf16 v[30:33], v[146:149], v[208:211], v[30:33]
	v_mfma_f32_16x16x32_bf16 v[18:21], v[138:141], v[216:219], v[18:21]
	v_mfma_f32_16x16x32_bf16 v[10:13], v[146:149], v[216:219], v[10:13]
	s_setprio 0
	s_setprio 1
	v_mfma_f32_16x16x32_bf16 v[58:61], v[150:153], v[166:169], v[58:61]
	v_mfma_f32_16x16x32_bf16 v[54:57], v[158:161], v[166:169], v[54:57]
	v_mfma_f32_16x16x32_bf16 v[42:45], v[150:153], v[174:177], v[42:45]
	v_mfma_f32_16x16x32_bf16 v[38:41], v[158:161], v[174:177], v[38:41]
	v_mfma_f32_16x16x32_bf16 v[26:29], v[150:153], v[204:207], v[26:29]
	v_mfma_f32_16x16x32_bf16 v[22:25], v[158:161], v[204:207], v[22:25]
	v_mfma_f32_16x16x32_bf16 v[6:9], v[150:153], v[212:215], v[6:9]
	v_mfma_f32_16x16x32_bf16 v[2:5], v[158:161], v[212:215], v[2:5]
	v_mfma_f32_16x16x32_bf16 v[58:61], v[154:157], v[170:173], v[58:61]
	v_mfma_f32_16x16x32_bf16 v[54:57], v[162:165], v[170:173], v[54:57]
	v_mfma_f32_16x16x32_bf16 v[42:45], v[154:157], v[178:181], v[42:45]
	v_mfma_f32_16x16x32_bf16 v[38:41], v[162:165], v[178:181], v[38:41]
	v_mfma_f32_16x16x32_bf16 v[26:29], v[154:157], v[208:211], v[26:29]
	v_mfma_f32_16x16x32_bf16 v[22:25], v[162:165], v[208:211], v[22:25]
	v_mfma_f32_16x16x32_bf16 v[6:9], v[154:157], v[216:219], v[6:9]
	v_mfma_f32_16x16x32_bf16 v[2:5], v[162:165], v[216:219], v[2:5]
	s_setprio 0
	s_barrier
	s_add_u32 s0, s0, 0x100
	s_addc_u32 s1, s1, 0
	s_add_u32 s40, s40, 0x100
	s_addc_u32 s41, s41, 0
	s_cmp_ge_i32 s42, s81
	s_mov_b32 s22, s42
	s_cbranch_scc0 .LBB0_271
	s_and_b64 vcc, exec, s[16:17]
	s_cbranch_vccnz .LBB0_278
